# MLA: waves 0-3 issue their tile writes in front of their 3rd PV MFMA (barrier still behind the 4th)
# speedup vs baseline: 1.0162x; 1.0162x over previous
; __device__ __forceinline__ void finishSM9(f32x16& p0, f32x16& p1, float alpha, float& l_reg, v8i32& p8) {
; #pragma unroll
;   for (int r = 0; r < 16; ++r) { p0[r] = __builtin_amdgcn_exp2f(p0[r]); p1[r] = __builtin_amdgcn_exp2f(p1[r]); }
;   float ps = 0;
; #pragma unroll
;   for (int r = 0; r < 16; ++r) ps += p0[r];
; #pragma unroll
;   for (int r = 0; r < 16; ++r) ps += p1[r];
;   { auto rr = __builtin_amdgcn_permlane32_swap(__float_as_uint(ps), __float_as_uint(ps), false, false);
;     ps = __uint_as_float(rr[0]) + __uint_as_float(rr[1]); }
;   l_reg = l_reg * alpha + ps;
; #pragma unroll
;   for (int g = 0; g < 4; ++g) {
;     int w = __builtin_amdgcn_cvt_pk_fp8_f32(p0[4 * g], p0[4 * g + 1], 0, false); p8[g] = __builtin_amdgcn_cvt_pk_fp8_f32(p0[4 * g + 2], p0[4 * g + 3], w, true);
;     int u = __builtin_amdgcn_cvt_pk_fp8_f32(p1[4 * g], p1[4 * g + 1], 0, false); p8[4 + g] = __builtin_amdgcn_cvt_pk_fp8_f32(p1[4 * g + 2], p1[4 * g + 3], u, true); }
; }
; __device__ __forceinline__ void pv8(f32x16* o, const char* Vt, const v8i32 p8, int r32, int hi) {
;   const int sw = (r32 >> 2) & 3, a0 = r32 * 64 + (((hi * 2) ^ sw) << 4), a1 = r32 * 64 + (((hi * 2 + 1) ^ sw) << 4);
; #pragma unroll
;   for (int d0 = 0; d0 < 4; ++d0) {
;     const v8i32 vf = cat8(*reinterpret_cast<const v4i32*>(Vt + d0 * 2048 + a0), *reinterpret_cast<const v4i32*>(Vt + d0 * 2048 + a1));
;     o[d0] = __builtin_amdgcn_mfma_scale_f32_32x32x64_f8f6f4(p8, vf, o[d0], 0, 0, 0, 127, 0, 127); }
; }
; __device__ __forceinline__ void qkt9(f32x16& p0, f32x16& p1, const char* Kn, const char* Kr, const v8i32* qf, const float init, int r32, int hi) {
; #pragma unroll
;   for (int r = 0; r < 16; ++r) { p0[r] = init; p1[r] = init; }
; #pragma unroll
;   for (int s = 0; s < 2; ++s) { const int c0 = s * 4 + hi * 2;
;     const v8i32 a0 = cat8(*reinterpret_cast<const v4i32*>(Kn + KN8SW(r32, c0)), *reinterpret_cast<const v4i32*>(Kn + KN8SW(r32, c0 + 1)));
;     const v8i32 a1 = cat8(*reinterpret_cast<const v4i32*>(Kn + 4096 + KN8SW(r32, c0)), *reinterpret_cast<const v4i32*>(Kn + 4096 + KN8SW(r32, c0 + 1)));
;     p0 = __builtin_amdgcn_mfma_scale_f32_32x32x64_f8f6f4(a0, qf[s], p0, 0, 0, 0, 127, 0, 124);
;     p1 = __builtin_amdgcn_mfma_scale_f32_32x32x64_f8f6f4(a1, qf[s], p1, 0, 0, 0, 127, 0, 124); }
;   { const int c0 = hi * 2;
.LBB0_1321:
	ds_read_b128 v[114:117], v215 offset:24576
	ds_read_b128 v[118:121], v216 offset:24576
	ds_read_b128 v[222:225], v215 offset:28672
	ds_read_b128 v[226:229], v216 offset:28672
	global_load_dwordx4 v[158:161], v176, s[18:19]
	global_load_dwordx4 v[162:165], v178, s[16:17]
	global_load_dwordx4 v[154:157], v[180:181], off
	v_add_u32_e32 v176, 0x2000, v176
	v_add_u32_e32 v178, 0x20000, v178
	s_mov_b64 s[20:21], 0x1000
	v_lshl_add_u64 v[180:181], v[180:181], 0, s[20:21]
	v_exp_f32_e32 v0, v82
	v_exp_f32_e32 v177, v83
	v_exp_f32_e32 v179, v84
	v_exp_f32_e32 v254, v85
	v_add_f32_e32 v219, v0, v177
	v_cvt_pk_fp8_f32 v246, v0, v177
	v_add_f32_e32 v219, v179, v219
	v_add_f32_e32 v219, v254, v219
	v_cvt_pk_fp8_f32 v246, v179, v254 op_sel:[0,0,1]
	s_waitcnt lgkmcnt(2)
	v_mfma_scale_f32_32x32x64_f8f6f4 v[114:129], v[114:121], v[146:153], v[230:245], v194, v193 op_sel_hi:[0,0,0]
	v_exp_f32_e32 v0, v86
	v_exp_f32_e32 v177, v87
	v_exp_f32_e32 v179, v88
	v_exp_f32_e32 v254, v89
	v_add_f32_e32 v219, v0, v219
	v_add_f32_e32 v219, v177, v219
	v_cvt_pk_fp8_f32 v247, v0, v177
	v_add_f32_e32 v219, v179, v219
	v_add_f32_e32 v219, v254, v219
	v_cvt_pk_fp8_f32 v247, v179, v254 op_sel:[0,0,1]
	ds_read_b128 v[82:85], v213 offset:24576
	ds_read_b128 v[86:89], v214 offset:24576
	s_waitcnt lgkmcnt(2)
	v_mfma_scale_f32_32x32x64_f8f6f4 v[98:113], v[222:229], v[146:153], v[230:245], v194, v193 op_sel_hi:[0,0,0]
	ds_read_b128 v[222:225], v213 offset:28672
	ds_read_b128 v[226:229], v214 offset:28672
	v_exp_f32_e32 v0, v90
	v_exp_f32_e32 v177, v91
	v_exp_f32_e32 v179, v92
	v_exp_f32_e32 v254, v93
	v_add_f32_e32 v219, v0, v219
	v_add_f32_e32 v219, v177, v219
	v_cvt_pk_fp8_f32 v248, v0, v177
	v_add_f32_e32 v219, v179, v219
	v_add_f32_e32 v219, v254, v219
	v_cvt_pk_fp8_f32 v248, v179, v254 op_sel:[0,0,1]
	v_exp_f32_e32 v0, v94
	v_exp_f32_e32 v177, v95
	v_exp_f32_e32 v179, v96
	v_exp_f32_e32 v254, v97
	v_add_f32_e32 v219, v0, v219
	v_add_f32_e32 v219, v177, v219
	v_cvt_pk_fp8_f32 v249, v0, v177
	v_add_f32_e32 v219, v179, v219
	v_add_f32_e32 v219, v254, v219
	v_cvt_pk_fp8_f32 v249, v179, v254 op_sel:[0,0,1]
	ds_read_b128 v[90:93], v185 offset:36864
	ds_read_b128 v[94:97], v186 offset:36864
	s_waitcnt lgkmcnt(4)
	v_mfma_scale_f32_32x32x64_f8f6f4 v[114:129], v[82:89], v[138:145], v[114:129], v194, v193 op_sel_hi:[0,0,0]
	v_exp_f32_e32 v0, v66
	v_exp_f32_e32 v177, v67
	v_exp_f32_e32 v179, v68
	v_exp_f32_e32 v254, v69
	v_add_f32_e32 v219, v0, v219
	v_add_f32_e32 v219, v177, v219
	v_cvt_pk_fp8_f32 v250, v0, v177
	v_add_f32_e32 v219, v179, v219
	v_add_f32_e32 v219, v254, v219
	v_cvt_pk_fp8_f32 v250, v179, v254 op_sel:[0,0,1]
	s_waitcnt lgkmcnt(2)
	v_mfma_scale_f32_32x32x64_f8f6f4 v[98:113], v[222:229], v[138:145], v[98:113], v194, v193 op_sel_hi:[0,0,0]
	ds_read_b128 v[222:225], v185 offset:38912
	ds_read_b128 v[226:229], v186 offset:38912
	v_exp_f32_e32 v0, v70
	v_exp_f32_e32 v177, v71
	v_exp_f32_e32 v179, v72
	v_exp_f32_e32 v254, v73
	v_add_f32_e32 v219, v0, v219
	v_add_f32_e32 v219, v177, v219
	v_cvt_pk_fp8_f32 v251, v0, v177
	v_add_f32_e32 v219, v179, v219
	v_add_f32_e32 v219, v254, v219
	v_cvt_pk_fp8_f32 v251, v179, v254 op_sel:[0,0,1]
	v_exp_f32_e32 v0, v74
	v_exp_f32_e32 v177, v75
	v_exp_f32_e32 v179, v76
	v_exp_f32_e32 v254, v77
	v_add_f32_e32 v219, v0, v219
	v_add_f32_e32 v219, v177, v219
	v_cvt_pk_fp8_f32 v252, v0, v177
	v_add_f32_e32 v219, v179, v219
	v_add_f32_e32 v219, v254, v219
	v_cvt_pk_fp8_f32 v252, v179, v254 op_sel:[0,0,1]
	s_waitcnt lgkmcnt(2)
	v_mfma_scale_f32_32x32x64_f8f6f4 v[114:129], v[90:97], v[130:137], v[114:129], v194, v193 op_sel_hi:[0,0,0]
	v_exp_f32_e32 v0, v78
	v_exp_f32_e32 v177, v79
	v_exp_f32_e32 v179, v80
	v_exp_f32_e32 v254, v81
	v_add_f32_e32 v219, v0, v219
	v_add_f32_e32 v219, v177, v219
	v_cvt_pk_fp8_f32 v253, v0, v177
	v_add_f32_e32 v219, v179, v219
	v_add_f32_e32 v219, v254, v219
	v_cvt_pk_fp8_f32 v253, v179, v254 op_sel:[0,0,1]
	ds_read_b128 v[90:93], v185 offset:0
	ds_read_b128 v[94:97], v186 offset:0
	ds_read_b128 v[82:85], v185 offset:2048
	ds_read_b128 v[86:89], v186 offset:2048
	ds_read_b128 v[74:77], v185 offset:4096
	ds_read_b128 v[78:81], v186 offset:4096
	ds_read_b128 v[66:69], v185 offset:6144
	ds_read_b128 v[70:73], v186 offset:6144
	s_waitcnt lgkmcnt(8)
	v_mfma_scale_f32_32x32x64_f8f6f4 v[98:113], v[222:229], v[130:137], v[98:113], v194, v193 op_sel_hi:[0,0,0]
	v_mov_b32_e32 v0, v219
	s_nop 1
	v_permlane32_swap_b32_e32 v219, v0
	v_add_f32_e32 v219, v219, v0
	v_fma_f32 v209, v209, v218, v219
	v_max_f32_e32 v177, v114, v115
	v_max3_f32 v177, v177, v116, v117
	v_max3_f32 v177, v177, v118, v119
	v_max3_f32 v177, v177, v120, v121
	v_max3_f32 v177, v177, v122, v123
	v_max3_f32 v177, v177, v124, v125
	v_max3_f32 v177, v177, v126, v127
	v_max3_f32 v177, v177, v128, v129
	s_waitcnt lgkmcnt(6)
	v_mfma_scale_f32_32x32x64_f8f6f4 v[50:65], v[246:253], v[90:97], v[50:65], v194, v194 op_sel_hi:[0,0,0]
	s_waitcnt lgkmcnt(4)
	v_mfma_scale_f32_32x32x64_f8f6f4 v[34:49], v[246:253], v[82:89], v[34:49], v194, v194 op_sel_hi:[0,0,0]
	s_waitcnt vmcnt(0)
	ds_write_b128 v210, v[158:161] offset:43008
	ds_write_b128 v211, v[162:165] offset:51200
	ds_write_b128 v212, v[154:157] offset:59392
	s_waitcnt lgkmcnt(5)
	v_mfma_scale_f32_32x32x64_f8f6f4 v[18:33], v[246:253], v[74:81], v[18:33], v194, v194 op_sel_hi:[0,0,0]
	s_waitcnt lgkmcnt(3)
	v_mfma_scale_f32_32x32x64_f8f6f4 v[2:17], v[246:253], v[66:73], v[2:17], v194, v194 op_sel_hi:[0,0,0]
	s_waitcnt lgkmcnt(0)
	s_barrier
	v_max_f32_e32 v0, v98, v99
	v_max3_f32 v0, v0, v100, v101
	v_max3_f32 v0, v0, v102, v103
	v_max3_f32 v0, v0, v104, v105
	v_max3_f32 v0, v0, v106, v107
	v_max3_f32 v0, v0, v108, v109
	v_max3_f32 v0, v0, v110, v111
	v_max3_f32 v0, v0, v112, v113
	v_max_f32_e32 v177, v177, v0
	v_mov_b32_e32 v0, v177
	v_mov_b32_e32 v221, 1.0
	s_nop 0
	v_permlane32_swap_b32_e32 v177, v0
	v_max_f32_e32 v177, v177, v0
	v_cmp_ge_f32_e32 vcc, s90, v177
	s_cmp_eq_u64 vcc, exec
	s_cbranch_scc0 .Lmla_h0_newmax
; __device__ __forceinline__ void finishSM9(f32x16& p0, f32x16& p1, float alpha, float& l_reg, v8i32& p8) {
; #pragma unroll
;   for (int r = 0; r < 16; ++r) { p0[r] = __builtin_amdgcn_exp2f(p0[r]); p1[r] = __builtin_amdgcn_exp2f(p1[r]); }
;   float ps = 0;
; #pragma unroll
;   for (int r = 0; r < 16; ++r) ps += p0[r];
; #pragma unroll
;   for (int r = 0; r < 16; ++r) ps += p1[r];
;   { auto rr = __builtin_amdgcn_permlane32_swap(__float_as_uint(ps), __float_as_uint(ps), false, false);
;     ps = __uint_as_float(rr[0]) + __uint_as_float(rr[1]); }
;   l_reg = l_reg * alpha + ps;
; #pragma unroll
;   for (int g = 0; g < 4; ++g) {
;     int w = __builtin_amdgcn_cvt_pk_fp8_f32(p0[4 * g], p0[4 * g + 1], 0, false); p8[g] = __builtin_amdgcn_cvt_pk_fp8_f32(p0[4 * g + 2], p0[4 * g + 3], w, true);
;     int u = __builtin_amdgcn_cvt_pk_fp8_f32(p1[4 * g], p1[4 * g + 1], 0, false); p8[4 + g] = __builtin_amdgcn_cvt_pk_fp8_f32(p1[4 * g + 2], p1[4 * g + 3], u, true); }
; }
; __device__ __forceinline__ void pv8(f32x16* o, const char* Vt, const v8i32 p8, int r32, int hi) {
;   const int sw = (r32 >> 2) & 3, a0 = r32 * 64 + (((hi * 2) ^ sw) << 4), a1 = r32 * 64 + (((hi * 2 + 1) ^ sw) << 4);
; #pragma unroll
;   for (int d0 = 0; d0 < 4; ++d0) {
;     const v8i32 vf = cat8(*reinterpret_cast<const v4i32*>(Vt + d0 * 2048 + a0), *reinterpret_cast<const v4i32*>(Vt + d0 * 2048 + a1));
;     o[d0] = __builtin_amdgcn_mfma_scale_f32_32x32x64_f8f6f4(p8, vf, o[d0], 0, 0, 0, 127, 0, 127); }
; }
; __device__ __forceinline__ void qkt9(f32x16& p0, f32x16& p1, const char* Kn, const char* Kr, const v8i32* qf, const float init, int r32, int hi) {
; #pragma unroll
;   for (int r = 0; r < 16; ++r) { p0[r] = init; p1[r] = init; }
; #pragma unroll
;   for (int s = 0; s < 2; ++s) { const int c0 = s * 4 + hi * 2;
;     const v8i32 a0 = cat8(*reinterpret_cast<const v4i32*>(Kn + KN8SW(r32, c0)), *reinterpret_cast<const v4i32*>(Kn + KN8SW(r32, c0 + 1)));
;     const v8i32 a1 = cat8(*reinterpret_cast<const v4i32*>(Kn + 4096 + KN8SW(r32, c0)), *reinterpret_cast<const v4i32*>(Kn + 4096 + KN8SW(r32, c0 + 1)));
;     p0 = __builtin_amdgcn_mfma_scale_f32_32x32x64_f8f6f4(a0, qf[s], p0, 0, 0, 0, 127, 0, 124);
;     p1 = __builtin_amdgcn_mfma_scale_f32_32x32x64_f8f6f4(a1, qf[s], p1, 0, 0, 0, 127, 0, 124); }
;   { const int c0 = hi * 2;
.Lmla_h0_cont:
	ds_read_b128 v[82:85], v215 offset:51200
	ds_read_b128 v[86:89], v216 offset:51200
	ds_read_b128 v[222:225], v215 offset:55296
	ds_read_b128 v[226:229], v216 offset:55296
	global_load_dwordx4 v[158:161], v176, s[18:19]
	global_load_dwordx4 v[162:165], v178, s[16:17]
	global_load_dwordx4 v[154:157], v[180:181], off
	v_add_u32_e32 v176, 0x2000, v176
	v_add_u32_e32 v178, 0x20000, v178
	s_mov_b64 s[20:21], 0x1000
	v_lshl_add_u64 v[180:181], v[180:181], 0, s[20:21]
	v_exp_f32_e32 v0, v114
	v_exp_f32_e32 v177, v115
	v_exp_f32_e32 v179, v116
	v_exp_f32_e32 v254, v117
	v_add_f32_e32 v219, v0, v177
	v_cvt_pk_fp8_f32 v246, v0, v177
	v_add_f32_e32 v219, v179, v219
	v_add_f32_e32 v219, v254, v219
	v_cvt_pk_fp8_f32 v246, v179, v254 op_sel:[0,0,1]
	s_waitcnt lgkmcnt(2)
	v_mfma_scale_f32_32x32x64_f8f6f4 v[82:97], v[82:89], v[146:153], v[230:245], v194, v193 op_sel_hi:[0,0,0]
	v_exp_f32_e32 v0, v118
	v_exp_f32_e32 v177, v119
	v_exp_f32_e32 v179, v120
	v_exp_f32_e32 v254, v121
	v_add_f32_e32 v219, v0, v219
	v_add_f32_e32 v219, v177, v219
	v_cvt_pk_fp8_f32 v247, v0, v177
	v_add_f32_e32 v219, v179, v219
	v_add_f32_e32 v219, v254, v219
	v_cvt_pk_fp8_f32 v247, v179, v254 op_sel:[0,0,1]
	ds_read_b128 v[114:117], v213 offset:51200
	ds_read_b128 v[118:121], v214 offset:51200
	s_waitcnt lgkmcnt(2)
	v_mfma_scale_f32_32x32x64_f8f6f4 v[66:81], v[222:229], v[146:153], v[230:245], v194, v193 op_sel_hi:[0,0,0]
	ds_read_b128 v[222:225], v213 offset:55296
	ds_read_b128 v[226:229], v214 offset:55296
	v_exp_f32_e32 v0, v122
	v_exp_f32_e32 v177, v123
	v_exp_f32_e32 v179, v124
	v_exp_f32_e32 v254, v125
	v_add_f32_e32 v219, v0, v219
	v_add_f32_e32 v219, v177, v219
	v_cvt_pk_fp8_f32 v248, v0, v177
	v_add_f32_e32 v219, v179, v219
	v_add_f32_e32 v219, v254, v219
	v_cvt_pk_fp8_f32 v248, v179, v254 op_sel:[0,0,1]
	v_exp_f32_e32 v0, v126
	v_exp_f32_e32 v177, v127
	v_exp_f32_e32 v179, v128
	v_exp_f32_e32 v254, v129
	v_add_f32_e32 v219, v0, v219
	v_add_f32_e32 v219, v177, v219
	v_cvt_pk_fp8_f32 v249, v0, v177
	v_add_f32_e32 v219, v179, v219
	v_add_f32_e32 v219, v254, v219
	v_cvt_pk_fp8_f32 v249, v179, v254 op_sel:[0,0,1]
	ds_read_b128 v[122:125], v185 offset:59392
	ds_read_b128 v[126:129], v186 offset:59392
	s_waitcnt lgkmcnt(4)
	v_mfma_scale_f32_32x32x64_f8f6f4 v[82:97], v[114:121], v[138:145], v[82:97], v194, v193 op_sel_hi:[0,0,0]
	v_exp_f32_e32 v0, v98
	v_exp_f32_e32 v177, v99
	v_exp_f32_e32 v179, v100
	v_exp_f32_e32 v254, v101
	v_add_f32_e32 v219, v0, v219
	v_add_f32_e32 v219, v177, v219
	v_cvt_pk_fp8_f32 v250, v0, v177
	v_add_f32_e32 v219, v179, v219
	v_add_f32_e32 v219, v254, v219
	v_cvt_pk_fp8_f32 v250, v179, v254 op_sel:[0,0,1]
	s_waitcnt lgkmcnt(2)
	v_mfma_scale_f32_32x32x64_f8f6f4 v[66:81], v[222:229], v[138:145], v[66:81], v194, v193 op_sel_hi:[0,0,0]
	ds_read_b128 v[222:225], v185 offset:61440
	ds_read_b128 v[226:229], v186 offset:61440
	v_exp_f32_e32 v0, v102
	v_exp_f32_e32 v177, v103
	v_exp_f32_e32 v179, v104
	v_exp_f32_e32 v254, v105
	v_add_f32_e32 v219, v0, v219
	v_add_f32_e32 v219, v177, v219
	v_cvt_pk_fp8_f32 v251, v0, v177
	v_add_f32_e32 v219, v179, v219
	v_add_f32_e32 v219, v254, v219
	v_cvt_pk_fp8_f32 v251, v179, v254 op_sel:[0,0,1]
	v_exp_f32_e32 v0, v106
	v_exp_f32_e32 v177, v107
	v_exp_f32_e32 v179, v108
	v_exp_f32_e32 v254, v109
	v_add_f32_e32 v219, v0, v219
	v_add_f32_e32 v219, v177, v219
	v_cvt_pk_fp8_f32 v252, v0, v177
	v_add_f32_e32 v219, v179, v219
	v_add_f32_e32 v219, v254, v219
	v_cvt_pk_fp8_f32 v252, v179, v254 op_sel:[0,0,1]
	s_waitcnt lgkmcnt(2)
	v_mfma_scale_f32_32x32x64_f8f6f4 v[82:97], v[122:129], v[130:137], v[82:97], v194, v193 op_sel_hi:[0,0,0]
	v_exp_f32_e32 v0, v110
	v_exp_f32_e32 v177, v111
	v_exp_f32_e32 v179, v112
	v_exp_f32_e32 v254, v113
	v_add_f32_e32 v219, v0, v219
	v_add_f32_e32 v219, v177, v219
	v_cvt_pk_fp8_f32 v253, v0, v177
	v_add_f32_e32 v219, v179, v219
	v_add_f32_e32 v219, v254, v219
	v_cvt_pk_fp8_f32 v253, v179, v254 op_sel:[0,0,1]
	ds_read_b128 v[122:125], v185 offset:8192
	ds_read_b128 v[126:129], v186 offset:8192
	ds_read_b128 v[114:117], v185 offset:10240
	ds_read_b128 v[118:121], v186 offset:10240
	ds_read_b128 v[106:109], v185 offset:12288
	ds_read_b128 v[110:113], v186 offset:12288
	ds_read_b128 v[98:101], v185 offset:14336
	ds_read_b128 v[102:105], v186 offset:14336
	s_waitcnt lgkmcnt(8)
	v_mfma_scale_f32_32x32x64_f8f6f4 v[66:81], v[222:229], v[130:137], v[66:81], v194, v193 op_sel_hi:[0,0,0]
	v_mov_b32_e32 v0, v219
	s_nop 1
	v_permlane32_swap_b32_e32 v219, v0
	v_add_f32_e32 v219, v219, v0
	v_fma_f32 v209, v209, v221, v219
	v_max_f32_e32 v177, v82, v83
	v_max3_f32 v177, v177, v84, v85
	v_max3_f32 v177, v177, v86, v87
	v_max3_f32 v177, v177, v88, v89
	v_max3_f32 v177, v177, v90, v91
	v_max3_f32 v177, v177, v92, v93
	v_max3_f32 v177, v177, v94, v95
	v_max3_f32 v177, v177, v96, v97
	s_waitcnt lgkmcnt(6)
	v_mfma_scale_f32_32x32x64_f8f6f4 v[50:65], v[246:253], v[122:129], v[50:65], v194, v194 op_sel_hi:[0,0,0]
	s_waitcnt lgkmcnt(4)
	v_mfma_scale_f32_32x32x64_f8f6f4 v[34:49], v[246:253], v[114:121], v[34:49], v194, v194 op_sel_hi:[0,0,0]
	s_waitcnt vmcnt(0)
	ds_write_b128 v210, v[158:161]
	ds_write_b128 v211, v[162:165] offset:16384
	ds_write_b128 v212, v[154:157] offset:32768
	s_waitcnt lgkmcnt(5)
	v_mfma_scale_f32_32x32x64_f8f6f4 v[18:33], v[246:253], v[106:113], v[18:33], v194, v194 op_sel_hi:[0,0,0]
	s_waitcnt lgkmcnt(3)
	v_mfma_scale_f32_32x32x64_f8f6f4 v[2:17], v[246:253], v[98:105], v[2:17], v194, v194 op_sel_hi:[0,0,0]
	s_waitcnt lgkmcnt(0)
	s_barrier
	v_max_f32_e32 v0, v66, v67
	v_max3_f32 v0, v0, v68, v69
	v_max3_f32 v0, v0, v70, v71
	v_max3_f32 v0, v0, v72, v73
	v_max3_f32 v0, v0, v74, v75
	v_max3_f32 v0, v0, v76, v77
	v_max3_f32 v0, v0, v78, v79
	v_max3_f32 v0, v0, v80, v81
	v_max_f32_e32 v177, v177, v0
	v_mov_b32_e32 v0, v177
	v_mov_b32_e32 v218, 1.0
	s_nop 0
	v_permlane32_swap_b32_e32 v177, v0
	v_max_f32_e32 v177, v177, v0
	v_cmp_ge_f32_e32 vcc, s90, v177
	s_cmp_eq_u64 vcc, exec
	s_cbranch_scc0 .Lmla_h1_newmax
; __device__ __forceinline__ void finishSM9(f32x16& p0, f32x16& p1, float alpha, float& l_reg, v8i32& p8) {
; #pragma unroll
;   for (int r = 0; r < 16; ++r) { p0[r] = __builtin_amdgcn_exp2f(p0[r]); p1[r] = __builtin_amdgcn_exp2f(p1[r]); }
;   float ps = 0;
; #pragma unroll
;   for (int r = 0; r < 16; ++r) ps += p0[r];
; #pragma unroll
;   for (int r = 0; r < 16; ++r) ps += p1[r];
;   { auto rr = __builtin_amdgcn_permlane32_swap(__float_as_uint(ps), __float_as_uint(ps), false, false);
;     ps = __uint_as_float(rr[0]) + __uint_as_float(rr[1]); }
;   l_reg = l_reg * alpha + ps;
; #pragma unroll
;   for (int g = 0; g < 4; ++g) {
;     int w = __builtin_amdgcn_cvt_pk_fp8_f32(p0[4 * g], p0[4 * g + 1], 0, false); p8[g] = __builtin_amdgcn_cvt_pk_fp8_f32(p0[4 * g + 2], p0[4 * g + 3], w, true);
;     int u = __builtin_amdgcn_cvt_pk_fp8_f32(p1[4 * g], p1[4 * g + 1], 0, false); p8[4 + g] = __builtin_amdgcn_cvt_pk_fp8_f32(p1[4 * g + 2], p1[4 * g + 3], u, true); }
; }
; __device__ __forceinline__ void pv8(f32x16* o, const char* Vt, const v8i32 p8, int r32, int hi) {
;   const int sw = (r32 >> 2) & 3, a0 = r32 * 64 + (((hi * 2) ^ sw) << 4), a1 = r32 * 64 + (((hi * 2 + 1) ^ sw) << 4);
; #pragma unroll
;   for (int d0 = 0; d0 < 4; ++d0) {
;     const v8i32 vf = cat8(*reinterpret_cast<const v4i32*>(Vt + d0 * 2048 + a0), *reinterpret_cast<const v4i32*>(Vt + d0 * 2048 + a1));
;     o[d0] = __builtin_amdgcn_mfma_scale_f32_32x32x64_f8f6f4(p8, vf, o[d0], 0, 0, 0, 127, 0, 127); }
; }
; __device__ __forceinline__ void qkt9(f32x16& p0, f32x16& p1, const char* Kn, const char* Kr, const v8i32* qf, const float init, int r32, int hi) {
; #pragma unroll
;   for (int r = 0; r < 16; ++r) { p0[r] = init; p1[r] = init; }
; #pragma unroll
;   for (int s = 0; s < 2; ++s) { const int c0 = s * 4 + hi * 2;
;     const v8i32 a0 = cat8(*reinterpret_cast<const v4i32*>(Kn + KN8SW(r32, c0)), *reinterpret_cast<const v4i32*>(Kn + KN8SW(r32, c0 + 1)));
;     const v8i32 a1 = cat8(*reinterpret_cast<const v4i32*>(Kn + 4096 + KN8SW(r32, c0)), *reinterpret_cast<const v4i32*>(Kn + 4096 + KN8SW(r32, c0 + 1)));
;     p0 = __builtin_amdgcn_mfma_scale_f32_32x32x64_f8f6f4(a0, qf[s], p0, 0, 0, 0, 127, 0, 124);
;     p1 = __builtin_amdgcn_mfma_scale_f32_32x32x64_f8f6f4(a1, qf[s], p1, 0, 0, 0, 127, 0, 124); }
;   { const int c0 = hi * 2;
.Lmla_h1_cont:
	ds_read_b128 v[114:117], v215 offset:16384
	ds_read_b128 v[118:121], v216 offset:16384
	ds_read_b128 v[222:225], v215 offset:20480
	ds_read_b128 v[226:229], v216 offset:20480
	global_load_dwordx4 v[158:161], v176, s[18:19]
	global_load_dwordx4 v[162:165], v178, s[16:17]
	global_load_dwordx4 v[154:157], v[180:181], off
	v_add_u32_e32 v176, 0x2000, v176
	v_add_u32_e32 v178, 0x20000, v178
	s_mov_b64 s[20:21], 0x1000
	v_lshl_add_u64 v[180:181], v[180:181], 0, s[20:21]
	v_exp_f32_e32 v0, v82
	v_exp_f32_e32 v177, v83
	v_exp_f32_e32 v179, v84
	v_exp_f32_e32 v254, v85
	v_add_f32_e32 v219, v0, v177
	v_cvt_pk_fp8_f32 v246, v0, v177
	v_add_f32_e32 v219, v179, v219
	v_add_f32_e32 v219, v254, v219
	v_cvt_pk_fp8_f32 v246, v179, v254 op_sel:[0,0,1]
	s_waitcnt lgkmcnt(2)
	v_mfma_scale_f32_32x32x64_f8f6f4 v[114:129], v[114:121], v[146:153], v[230:245], v194, v193 op_sel_hi:[0,0,0]
	v_exp_f32_e32 v0, v86
	v_exp_f32_e32 v177, v87
	v_exp_f32_e32 v179, v88
	v_exp_f32_e32 v254, v89
	v_add_f32_e32 v219, v0, v219
	v_add_f32_e32 v219, v177, v219
	v_cvt_pk_fp8_f32 v247, v0, v177
	v_add_f32_e32 v219, v179, v219
	v_add_f32_e32 v219, v254, v219
	v_cvt_pk_fp8_f32 v247, v179, v254 op_sel:[0,0,1]
	ds_read_b128 v[82:85], v213 offset:16384
	ds_read_b128 v[86:89], v214 offset:16384
	s_waitcnt lgkmcnt(2)
	v_mfma_scale_f32_32x32x64_f8f6f4 v[98:113], v[222:229], v[146:153], v[230:245], v194, v193 op_sel_hi:[0,0,0]
	ds_read_b128 v[222:225], v213 offset:20480
	ds_read_b128 v[226:229], v214 offset:20480
	v_exp_f32_e32 v0, v90
	v_exp_f32_e32 v177, v91
	v_exp_f32_e32 v179, v92
	v_exp_f32_e32 v254, v93
	v_add_f32_e32 v219, v0, v219
	v_add_f32_e32 v219, v177, v219
	v_cvt_pk_fp8_f32 v248, v0, v177
	v_add_f32_e32 v219, v179, v219
	v_add_f32_e32 v219, v254, v219
	v_cvt_pk_fp8_f32 v248, v179, v254 op_sel:[0,0,1]
	v_exp_f32_e32 v0, v94
	v_exp_f32_e32 v177, v95
	v_exp_f32_e32 v179, v96
	v_exp_f32_e32 v254, v97
	v_add_f32_e32 v219, v0, v219
	v_add_f32_e32 v219, v177, v219
	v_cvt_pk_fp8_f32 v249, v0, v177
	v_add_f32_e32 v219, v179, v219
	v_add_f32_e32 v219, v254, v219
	v_cvt_pk_fp8_f32 v249, v179, v254 op_sel:[0,0,1]
	ds_read_b128 v[90:93], v185 offset:32768
	ds_read_b128 v[94:97], v186 offset:32768
	s_waitcnt lgkmcnt(4)
	v_mfma_scale_f32_32x32x64_f8f6f4 v[114:129], v[82:89], v[138:145], v[114:129], v194, v193 op_sel_hi:[0,0,0]
	v_exp_f32_e32 v0, v66
	v_exp_f32_e32 v177, v67
	v_exp_f32_e32 v179, v68
	v_exp_f32_e32 v254, v69
	v_add_f32_e32 v219, v0, v219
	v_add_f32_e32 v219, v177, v219
	v_cvt_pk_fp8_f32 v250, v0, v177
	v_add_f32_e32 v219, v179, v219
	v_add_f32_e32 v219, v254, v219
	v_cvt_pk_fp8_f32 v250, v179, v254 op_sel:[0,0,1]
	s_waitcnt lgkmcnt(2)
	v_mfma_scale_f32_32x32x64_f8f6f4 v[98:113], v[222:229], v[138:145], v[98:113], v194, v193 op_sel_hi:[0,0,0]
	ds_read_b128 v[222:225], v185 offset:34816
	ds_read_b128 v[226:229], v186 offset:34816
	v_exp_f32_e32 v0, v70
	v_exp_f32_e32 v177, v71
	v_exp_f32_e32 v179, v72
	v_exp_f32_e32 v254, v73
	v_add_f32_e32 v219, v0, v219
	v_add_f32_e32 v219, v177, v219
	v_cvt_pk_fp8_f32 v251, v0, v177
	v_add_f32_e32 v219, v179, v219
	v_add_f32_e32 v219, v254, v219
	v_cvt_pk_fp8_f32 v251, v179, v254 op_sel:[0,0,1]
	v_exp_f32_e32 v0, v74
	v_exp_f32_e32 v177, v75
	v_exp_f32_e32 v179, v76
	v_exp_f32_e32 v254, v77
	v_add_f32_e32 v219, v0, v219
	v_add_f32_e32 v219, v177, v219
	v_cvt_pk_fp8_f32 v252, v0, v177
	v_add_f32_e32 v219, v179, v219
	v_add_f32_e32 v219, v254, v219
	v_cvt_pk_fp8_f32 v252, v179, v254 op_sel:[0,0,1]
	s_waitcnt lgkmcnt(2)
	v_mfma_scale_f32_32x32x64_f8f6f4 v[114:129], v[90:97], v[130:137], v[114:129], v194, v193 op_sel_hi:[0,0,0]
	v_exp_f32_e32 v0, v78
	v_exp_f32_e32 v177, v79
	v_exp_f32_e32 v179, v80
	v_exp_f32_e32 v254, v81
	v_add_f32_e32 v219, v0, v219
	v_add_f32_e32 v219, v177, v219
	v_cvt_pk_fp8_f32 v253, v0, v177
	v_add_f32_e32 v219, v179, v219
	v_add_f32_e32 v219, v254, v219
	v_cvt_pk_fp8_f32 v253, v179, v254 op_sel:[0,0,1]
	ds_read_b128 v[90:93], v185 offset:43008
	ds_read_b128 v[94:97], v186 offset:43008
	ds_read_b128 v[82:85], v185 offset:45056
	ds_read_b128 v[86:89], v186 offset:45056
	ds_read_b128 v[74:77], v185 offset:47104
	ds_read_b128 v[78:81], v186 offset:47104
	ds_read_b128 v[66:69], v185 offset:49152
	ds_read_b128 v[70:73], v186 offset:49152
	s_waitcnt lgkmcnt(8)
	v_mfma_scale_f32_32x32x64_f8f6f4 v[98:113], v[222:229], v[130:137], v[98:113], v194, v193 op_sel_hi:[0,0,0]
	v_mov_b32_e32 v0, v219
	s_nop 1
	v_permlane32_swap_b32_e32 v219, v0
	v_add_f32_e32 v219, v219, v0
	v_fma_f32 v209, v209, v218, v219
	v_max_f32_e32 v177, v114, v115
	v_max3_f32 v177, v177, v116, v117
	v_max3_f32 v177, v177, v118, v119
	v_max3_f32 v177, v177, v120, v121
	v_max3_f32 v177, v177, v122, v123
	v_max3_f32 v177, v177, v124, v125
	v_max3_f32 v177, v177, v126, v127
	v_max3_f32 v177, v177, v128, v129
	s_waitcnt lgkmcnt(6)
	v_mfma_scale_f32_32x32x64_f8f6f4 v[50:65], v[246:253], v[90:97], v[50:65], v194, v194 op_sel_hi:[0,0,0]
	s_waitcnt lgkmcnt(4)
	v_mfma_scale_f32_32x32x64_f8f6f4 v[34:49], v[246:253], v[82:89], v[34:49], v194, v194 op_sel_hi:[0,0,0]
	s_waitcnt vmcnt(0)
	ds_write_b128 v210, v[158:161] offset:8192
	ds_write_b128 v211, v[162:165] offset:24576
	ds_write_b128 v212, v[154:157] offset:36864
	s_waitcnt lgkmcnt(5)
	v_mfma_scale_f32_32x32x64_f8f6f4 v[18:33], v[246:253], v[74:81], v[18:33], v194, v194 op_sel_hi:[0,0,0]
	s_waitcnt lgkmcnt(3)
	v_mfma_scale_f32_32x32x64_f8f6f4 v[2:17], v[246:253], v[66:73], v[2:17], v194, v194 op_sel_hi:[0,0,0]
	s_waitcnt lgkmcnt(0)
	s_barrier
	v_max_f32_e32 v0, v98, v99
	v_max3_f32 v0, v0, v100, v101
	v_max3_f32 v0, v0, v102, v103
	v_max3_f32 v0, v0, v104, v105
	v_max3_f32 v0, v0, v106, v107
	v_max3_f32 v0, v0, v108, v109
	v_max3_f32 v0, v0, v110, v111
	v_max3_f32 v0, v0, v112, v113
	v_max_f32_e32 v177, v177, v0
	v_mov_b32_e32 v0, v177
	v_mov_b32_e32 v221, 1.0
	s_nop 0
	v_permlane32_swap_b32_e32 v177, v0
	v_max_f32_e32 v177, v177, v0
	v_cmp_ge_f32_e32 vcc, s90, v177
	s_cmp_eq_u64 vcc, exec
	s_cbranch_scc0 .Lmla_h2_newmax
; __device__ __forceinline__ void finishSM9(f32x16& p0, f32x16& p1, float alpha, float& l_reg, v8i32& p8) {
; #pragma unroll
;   for (int r = 0; r < 16; ++r) { p0[r] = __builtin_amdgcn_exp2f(p0[r]); p1[r] = __builtin_amdgcn_exp2f(p1[r]); }
;   float ps = 0;
; #pragma unroll
;   for (int r = 0; r < 16; ++r) ps += p0[r];
; #pragma unroll
;   for (int r = 0; r < 16; ++r) ps += p1[r];
;   { auto rr = __builtin_amdgcn_permlane32_swap(__float_as_uint(ps), __float_as_uint(ps), false, false);
;     ps = __uint_as_float(rr[0]) + __uint_as_float(rr[1]); }
;   l_reg = l_reg * alpha + ps;
; #pragma unroll
;   for (int g = 0; g < 4; ++g) {
;     int w = __builtin_amdgcn_cvt_pk_fp8_f32(p0[4 * g], p0[4 * g + 1], 0, false); p8[g] = __builtin_amdgcn_cvt_pk_fp8_f32(p0[4 * g + 2], p0[4 * g + 3], w, true);
;     int u = __builtin_amdgcn_cvt_pk_fp8_f32(p1[4 * g], p1[4 * g + 1], 0, false); p8[4 + g] = __builtin_amdgcn_cvt_pk_fp8_f32(p1[4 * g + 2], p1[4 * g + 3], u, true); }
; }
; __device__ __forceinline__ void pv8(f32x16* o, const char* Vt, const v8i32 p8, int r32, int hi) {
;   const int sw = (r32 >> 2) & 3, a0 = r32 * 64 + (((hi * 2) ^ sw) << 4), a1 = r32 * 64 + (((hi * 2 + 1) ^ sw) << 4);
; #pragma unroll
;   for (int d0 = 0; d0 < 4; ++d0) {
;     const v8i32 vf = cat8(*reinterpret_cast<const v4i32*>(Vt + d0 * 2048 + a0), *reinterpret_cast<const v4i32*>(Vt + d0 * 2048 + a1));
;     o[d0] = __builtin_amdgcn_mfma_scale_f32_32x32x64_f8f6f4(p8, vf, o[d0], 0, 0, 0, 127, 0, 127); }
; }
; __device__ __forceinline__ void qkt9(f32x16& p0, f32x16& p1, const char* Kn, const char* Kr, const v8i32* qf, const float init, int r32, int hi) {
; #pragma unroll
;   for (int r = 0; r < 16; ++r) { p0[r] = init; p1[r] = init; }
; #pragma unroll
;   for (int s = 0; s < 2; ++s) { const int c0 = s * 4 + hi * 2;
;     const v8i32 a0 = cat8(*reinterpret_cast<const v4i32*>(Kn + KN8SW(r32, c0)), *reinterpret_cast<const v4i32*>(Kn + KN8SW(r32, c0 + 1)));
;     const v8i32 a1 = cat8(*reinterpret_cast<const v4i32*>(Kn + 4096 + KN8SW(r32, c0)), *reinterpret_cast<const v4i32*>(Kn + 4096 + KN8SW(r32, c0 + 1)));
;     p0 = __builtin_amdgcn_mfma_scale_f32_32x32x64_f8f6f4(a0, qf[s], p0, 0, 0, 0, 127, 0, 124);
;     p1 = __builtin_amdgcn_mfma_scale_f32_32x32x64_f8f6f4(a1, qf[s], p1, 0, 0, 0, 127, 0, 124); }
;   { const int c0 = hi * 2;
.Lmla_h2_cont:
	ds_read_b128 v[82:85], v215 offset:24576
	ds_read_b128 v[86:89], v216 offset:24576
	ds_read_b128 v[222:225], v215 offset:28672
	ds_read_b128 v[226:229], v216 offset:28672
	global_load_dwordx4 v[158:161], v176, s[18:19]
	global_load_dwordx4 v[162:165], v178, s[16:17]
	global_load_dwordx4 v[154:157], v[180:181], off
	v_add_u32_e32 v176, 0x2000, v176
	v_add_u32_e32 v178, 0x20000, v178
	s_mov_b64 s[20:21], 0x1000
	v_lshl_add_u64 v[180:181], v[180:181], 0, s[20:21]
	v_exp_f32_e32 v0, v114
	v_exp_f32_e32 v177, v115
	v_exp_f32_e32 v179, v116
	v_exp_f32_e32 v254, v117
	v_add_f32_e32 v219, v0, v177
	v_cvt_pk_fp8_f32 v246, v0, v177
	v_add_f32_e32 v219, v179, v219
	v_add_f32_e32 v219, v254, v219
	v_cvt_pk_fp8_f32 v246, v179, v254 op_sel:[0,0,1]
	s_waitcnt lgkmcnt(2)
	v_mfma_scale_f32_32x32x64_f8f6f4 v[82:97], v[82:89], v[146:153], v[230:245], v194, v193 op_sel_hi:[0,0,0]
	v_exp_f32_e32 v0, v118
	v_exp_f32_e32 v177, v119
	v_exp_f32_e32 v179, v120
	v_exp_f32_e32 v254, v121
	v_add_f32_e32 v219, v0, v219
	v_add_f32_e32 v219, v177, v219
	v_cvt_pk_fp8_f32 v247, v0, v177
	v_add_f32_e32 v219, v179, v219
	v_add_f32_e32 v219, v254, v219
	v_cvt_pk_fp8_f32 v247, v179, v254 op_sel:[0,0,1]
	ds_read_b128 v[114:117], v213 offset:24576
	ds_read_b128 v[118:121], v214 offset:24576
	s_waitcnt lgkmcnt(2)
	v_mfma_scale_f32_32x32x64_f8f6f4 v[66:81], v[222:229], v[146:153], v[230:245], v194, v193 op_sel_hi:[0,0,0]
	ds_read_b128 v[222:225], v213 offset:28672
	ds_read_b128 v[226:229], v214 offset:28672
	v_exp_f32_e32 v0, v122
	v_exp_f32_e32 v177, v123
	v_exp_f32_e32 v179, v124
	v_exp_f32_e32 v254, v125
	v_add_f32_e32 v219, v0, v219
	v_add_f32_e32 v219, v177, v219
	v_cvt_pk_fp8_f32 v248, v0, v177
	v_add_f32_e32 v219, v179, v219
	v_add_f32_e32 v219, v254, v219
	v_cvt_pk_fp8_f32 v248, v179, v254 op_sel:[0,0,1]
	v_exp_f32_e32 v0, v126
	v_exp_f32_e32 v177, v127
	v_exp_f32_e32 v179, v128
	v_exp_f32_e32 v254, v129
	v_add_f32_e32 v219, v0, v219
	v_add_f32_e32 v219, v177, v219
	v_cvt_pk_fp8_f32 v249, v0, v177
	v_add_f32_e32 v219, v179, v219
	v_add_f32_e32 v219, v254, v219
	v_cvt_pk_fp8_f32 v249, v179, v254 op_sel:[0,0,1]
	ds_read_b128 v[122:125], v185 offset:36864
	ds_read_b128 v[126:129], v186 offset:36864
	s_waitcnt lgkmcnt(4)
	v_mfma_scale_f32_32x32x64_f8f6f4 v[82:97], v[114:121], v[138:145], v[82:97], v194, v193 op_sel_hi:[0,0,0]
	v_exp_f32_e32 v0, v98
	v_exp_f32_e32 v177, v99
	v_exp_f32_e32 v179, v100
	v_exp_f32_e32 v254, v101
	v_add_f32_e32 v219, v0, v219
	v_add_f32_e32 v219, v177, v219
	v_cvt_pk_fp8_f32 v250, v0, v177
	v_add_f32_e32 v219, v179, v219
	v_add_f32_e32 v219, v254, v219
	v_cvt_pk_fp8_f32 v250, v179, v254 op_sel:[0,0,1]
	s_waitcnt lgkmcnt(2)
	v_mfma_scale_f32_32x32x64_f8f6f4 v[66:81], v[222:229], v[138:145], v[66:81], v194, v193 op_sel_hi:[0,0,0]
	ds_read_b128 v[222:225], v185 offset:38912
	ds_read_b128 v[226:229], v186 offset:38912
	v_exp_f32_e32 v0, v102
	v_exp_f32_e32 v177, v103
	v_exp_f32_e32 v179, v104
	v_exp_f32_e32 v254, v105
	v_add_f32_e32 v219, v0, v219
	v_add_f32_e32 v219, v177, v219
	v_cvt_pk_fp8_f32 v251, v0, v177
	v_add_f32_e32 v219, v179, v219
	v_add_f32_e32 v219, v254, v219
	v_cvt_pk_fp8_f32 v251, v179, v254 op_sel:[0,0,1]
	v_exp_f32_e32 v0, v106
	v_exp_f32_e32 v177, v107
	v_exp_f32_e32 v179, v108
	v_exp_f32_e32 v254, v109
	v_add_f32_e32 v219, v0, v219
	v_add_f32_e32 v219, v177, v219
	v_cvt_pk_fp8_f32 v252, v0, v177
	v_add_f32_e32 v219, v179, v219
	v_add_f32_e32 v219, v254, v219
	v_cvt_pk_fp8_f32 v252, v179, v254 op_sel:[0,0,1]
	s_waitcnt lgkmcnt(2)
	v_mfma_scale_f32_32x32x64_f8f6f4 v[82:97], v[122:129], v[130:137], v[82:97], v194, v193 op_sel_hi:[0,0,0]
	v_exp_f32_e32 v0, v110
	v_exp_f32_e32 v177, v111
	v_exp_f32_e32 v179, v112
	v_exp_f32_e32 v254, v113
	v_add_f32_e32 v219, v0, v219
	v_add_f32_e32 v219, v177, v219
	v_cvt_pk_fp8_f32 v253, v0, v177
	v_add_f32_e32 v219, v179, v219
	v_add_f32_e32 v219, v254, v219
	v_cvt_pk_fp8_f32 v253, v179, v254 op_sel:[0,0,1]
	ds_read_b128 v[122:125], v185 offset:0
	ds_read_b128 v[126:129], v186 offset:0
	ds_read_b128 v[114:117], v185 offset:2048
	ds_read_b128 v[118:121], v186 offset:2048
	ds_read_b128 v[106:109], v185 offset:4096
	ds_read_b128 v[110:113], v186 offset:4096
	ds_read_b128 v[98:101], v185 offset:6144
	ds_read_b128 v[102:105], v186 offset:6144
	s_waitcnt lgkmcnt(8)
	v_mfma_scale_f32_32x32x64_f8f6f4 v[66:81], v[222:229], v[130:137], v[66:81], v194, v193 op_sel_hi:[0,0,0]
	v_mov_b32_e32 v0, v219
	s_nop 1
	v_permlane32_swap_b32_e32 v219, v0
	v_add_f32_e32 v219, v219, v0
	v_fma_f32 v209, v209, v221, v219
	v_max_f32_e32 v177, v82, v83
	v_max3_f32 v177, v177, v84, v85
	v_max3_f32 v177, v177, v86, v87
	v_max3_f32 v177, v177, v88, v89
	v_max3_f32 v177, v177, v90, v91
	v_max3_f32 v177, v177, v92, v93
	v_max3_f32 v177, v177, v94, v95
	v_max3_f32 v177, v177, v96, v97
	s_waitcnt lgkmcnt(6)
	v_mfma_scale_f32_32x32x64_f8f6f4 v[50:65], v[246:253], v[122:129], v[50:65], v194, v194 op_sel_hi:[0,0,0]
	s_waitcnt lgkmcnt(4)
	v_mfma_scale_f32_32x32x64_f8f6f4 v[34:49], v[246:253], v[114:121], v[34:49], v194, v194 op_sel_hi:[0,0,0]
	s_waitcnt vmcnt(0)
	ds_write_b128 v210, v[158:161] offset:43008
	ds_write_b128 v211, v[162:165] offset:51200
	ds_write_b128 v212, v[154:157] offset:59392
	s_waitcnt lgkmcnt(5)
	v_mfma_scale_f32_32x32x64_f8f6f4 v[18:33], v[246:253], v[106:113], v[18:33], v194, v194 op_sel_hi:[0,0,0]
	s_waitcnt lgkmcnt(3)
	v_mfma_scale_f32_32x32x64_f8f6f4 v[2:17], v[246:253], v[98:105], v[2:17], v194, v194 op_sel_hi:[0,0,0]
	s_waitcnt lgkmcnt(0)
	s_barrier
	v_max_f32_e32 v0, v66, v67
	v_max3_f32 v0, v0, v68, v69
	v_max3_f32 v0, v0, v70, v71
	v_max3_f32 v0, v0, v72, v73
	v_max3_f32 v0, v0, v74, v75
	v_max3_f32 v0, v0, v76, v77
	v_max3_f32 v0, v0, v78, v79
	v_max3_f32 v0, v0, v80, v81
	v_max_f32_e32 v177, v177, v0
	v_mov_b32_e32 v0, v177
	v_mov_b32_e32 v218, 1.0
	s_nop 0
	v_permlane32_swap_b32_e32 v177, v0
	v_max_f32_e32 v177, v177, v0
	v_cmp_ge_f32_e32 vcc, s90, v177
	s_cmp_eq_u64 vcc, exec
	s_cbranch_scc0 .Lmla_h3_newmax
; __device__ __forceinline__ void finishSM9(f32x16& p0, f32x16& p1, float alpha, float& l_reg, v8i32& p8) {
; #pragma unroll
;   for (int r = 0; r < 16; ++r) { p0[r] = __builtin_amdgcn_exp2f(p0[r]); p1[r] = __builtin_amdgcn_exp2f(p1[r]); }
;   float ps = 0;
; #pragma unroll
;   for (int r = 0; r < 16; ++r) ps += p0[r];
; #pragma unroll
;   for (int r = 0; r < 16; ++r) ps += p1[r];
;   { auto rr = __builtin_amdgcn_permlane32_swap(__float_as_uint(ps), __float_as_uint(ps), false, false);
;     ps = __uint_as_float(rr[0]) + __uint_as_float(rr[1]); }
;   l_reg = l_reg * alpha + ps;
; #pragma unroll
;   for (int g = 0; g < 4; ++g) {
;     int w = __builtin_amdgcn_cvt_pk_fp8_f32(p0[4 * g], p0[4 * g + 1], 0, false); p8[g] = __builtin_amdgcn_cvt_pk_fp8_f32(p0[4 * g + 2], p0[4 * g + 3], w, true);
;     int u = __builtin_amdgcn_cvt_pk_fp8_f32(p1[4 * g], p1[4 * g + 1], 0, false); p8[4 + g] = __builtin_amdgcn_cvt_pk_fp8_f32(p1[4 * g + 2], p1[4 * g + 3], u, true); }
; }
; __device__ __forceinline__ void pv8(f32x16* o, const char* Vt, const v8i32 p8, int r32, int hi) {
;   const int sw = (r32 >> 2) & 3, a0 = r32 * 64 + (((hi * 2) ^ sw) << 4), a1 = r32 * 64 + (((hi * 2 + 1) ^ sw) << 4);
; #pragma unroll
;   for (int d0 = 0; d0 < 4; ++d0) {
;     const v8i32 vf = cat8(*reinterpret_cast<const v4i32*>(Vt + d0 * 2048 + a0), *reinterpret_cast<const v4i32*>(Vt + d0 * 2048 + a1));
;     o[d0] = __builtin_amdgcn_mfma_scale_f32_32x32x64_f8f6f4(p8, vf, o[d0], 0, 0, 0, 127, 0, 127); }
; }
; __device__ __forceinline__ void qkt9(f32x16& p0, f32x16& p1, const char* Kn, const char* Kr, const v8i32* qf, const float init, int r32, int hi) {
; #pragma unroll
;   for (int r = 0; r < 16; ++r) { p0[r] = init; p1[r] = init; }
; #pragma unroll
;   for (int s = 0; s < 2; ++s) { const int c0 = s * 4 + hi * 2;
;     const v8i32 a0 = cat8(*reinterpret_cast<const v4i32*>(Kn + KN8SW(r32, c0)), *reinterpret_cast<const v4i32*>(Kn + KN8SW(r32, c0 + 1)));
;     const v8i32 a1 = cat8(*reinterpret_cast<const v4i32*>(Kn + 4096 + KN8SW(r32, c0)), *reinterpret_cast<const v4i32*>(Kn + 4096 + KN8SW(r32, c0 + 1)));
;     p0 = __builtin_amdgcn_mfma_scale_f32_32x32x64_f8f6f4(a0, qf[s], p0, 0, 0, 0, 127, 0, 124);
;     p1 = __builtin_amdgcn_mfma_scale_f32_32x32x64_f8f6f4(a1, qf[s], p1, 0, 0, 0, 127, 0, 124); }
;   { const int c0 = hi * 2;
.Lmla_h3_cont:
	ds_read_b128 v[114:117], v215 offset:51200
	ds_read_b128 v[118:121], v216 offset:51200
	ds_read_b128 v[222:225], v215 offset:55296
	ds_read_b128 v[226:229], v216 offset:55296
	global_load_dwordx4 v[158:161], v176, s[18:19]
	global_load_dwordx4 v[162:165], v178, s[16:17]
	global_load_dwordx4 v[154:157], v[180:181], off
	v_add_u32_e32 v176, 0x2000, v176
	v_add_u32_e32 v178, 0x20000, v178
	s_mov_b64 s[20:21], 0x1000
	v_lshl_add_u64 v[180:181], v[180:181], 0, s[20:21]
	v_exp_f32_e32 v0, v82
	v_exp_f32_e32 v177, v83
	v_exp_f32_e32 v179, v84
	v_exp_f32_e32 v254, v85
	v_add_f32_e32 v219, v0, v177
	v_cvt_pk_fp8_f32 v246, v0, v177
	v_add_f32_e32 v219, v179, v219
	v_add_f32_e32 v219, v254, v219
	v_cvt_pk_fp8_f32 v246, v179, v254 op_sel:[0,0,1]
	s_waitcnt lgkmcnt(2)
	v_mfma_scale_f32_32x32x64_f8f6f4 v[114:129], v[114:121], v[146:153], v[230:245], v194, v193 op_sel_hi:[0,0,0]
	v_exp_f32_e32 v0, v86
	v_exp_f32_e32 v177, v87
	v_exp_f32_e32 v179, v88
	v_exp_f32_e32 v254, v89
	v_add_f32_e32 v219, v0, v219
	v_add_f32_e32 v219, v177, v219
	v_cvt_pk_fp8_f32 v247, v0, v177
	v_add_f32_e32 v219, v179, v219
	v_add_f32_e32 v219, v254, v219
	v_cvt_pk_fp8_f32 v247, v179, v254 op_sel:[0,0,1]
	ds_read_b128 v[82:85], v213 offset:51200
	ds_read_b128 v[86:89], v214 offset:51200
	s_waitcnt lgkmcnt(2)
	v_mfma_scale_f32_32x32x64_f8f6f4 v[98:113], v[222:229], v[146:153], v[230:245], v194, v193 op_sel_hi:[0,0,0]
	ds_read_b128 v[222:225], v213 offset:55296
	ds_read_b128 v[226:229], v214 offset:55296
	v_exp_f32_e32 v0, v90
	v_exp_f32_e32 v177, v91
	v_exp_f32_e32 v179, v92
	v_exp_f32_e32 v254, v93
	v_add_f32_e32 v219, v0, v219
	v_add_f32_e32 v219, v177, v219
	v_cvt_pk_fp8_f32 v248, v0, v177
	v_add_f32_e32 v219, v179, v219
	v_add_f32_e32 v219, v254, v219
	v_cvt_pk_fp8_f32 v248, v179, v254 op_sel:[0,0,1]
	v_exp_f32_e32 v0, v94
	v_exp_f32_e32 v177, v95
	v_exp_f32_e32 v179, v96
	v_exp_f32_e32 v254, v97
	v_add_f32_e32 v219, v0, v219
	v_add_f32_e32 v219, v177, v219
	v_cvt_pk_fp8_f32 v249, v0, v177
	v_add_f32_e32 v219, v179, v219
	v_add_f32_e32 v219, v254, v219
	v_cvt_pk_fp8_f32 v249, v179, v254 op_sel:[0,0,1]
	ds_read_b128 v[90:93], v185 offset:59392
	ds_read_b128 v[94:97], v186 offset:59392
	s_waitcnt lgkmcnt(4)
	v_mfma_scale_f32_32x32x64_f8f6f4 v[114:129], v[82:89], v[138:145], v[114:129], v194, v193 op_sel_hi:[0,0,0]
	v_exp_f32_e32 v0, v66
	v_exp_f32_e32 v177, v67
	v_exp_f32_e32 v179, v68
	v_exp_f32_e32 v254, v69
	v_add_f32_e32 v219, v0, v219
	v_add_f32_e32 v219, v177, v219
	v_cvt_pk_fp8_f32 v250, v0, v177
	v_add_f32_e32 v219, v179, v219
	v_add_f32_e32 v219, v254, v219
	v_cvt_pk_fp8_f32 v250, v179, v254 op_sel:[0,0,1]
	s_waitcnt lgkmcnt(2)
	v_mfma_scale_f32_32x32x64_f8f6f4 v[98:113], v[222:229], v[138:145], v[98:113], v194, v193 op_sel_hi:[0,0,0]
	ds_read_b128 v[222:225], v185 offset:61440
	ds_read_b128 v[226:229], v186 offset:61440
	v_exp_f32_e32 v0, v70
	v_exp_f32_e32 v177, v71
	v_exp_f32_e32 v179, v72
	v_exp_f32_e32 v254, v73
	v_add_f32_e32 v219, v0, v219
	v_add_f32_e32 v219, v177, v219
	v_cvt_pk_fp8_f32 v251, v0, v177
	v_add_f32_e32 v219, v179, v219
	v_add_f32_e32 v219, v254, v219
	v_cvt_pk_fp8_f32 v251, v179, v254 op_sel:[0,0,1]
	v_exp_f32_e32 v0, v74
	v_exp_f32_e32 v177, v75
	v_exp_f32_e32 v179, v76
	v_exp_f32_e32 v254, v77
	v_add_f32_e32 v219, v0, v219
	v_add_f32_e32 v219, v177, v219
	v_cvt_pk_fp8_f32 v252, v0, v177
	v_add_f32_e32 v219, v179, v219
	v_add_f32_e32 v219, v254, v219
	v_cvt_pk_fp8_f32 v252, v179, v254 op_sel:[0,0,1]
	s_waitcnt lgkmcnt(2)
	v_mfma_scale_f32_32x32x64_f8f6f4 v[114:129], v[90:97], v[130:137], v[114:129], v194, v193 op_sel_hi:[0,0,0]
	v_exp_f32_e32 v0, v78
	v_exp_f32_e32 v177, v79
	v_exp_f32_e32 v179, v80
	v_exp_f32_e32 v254, v81
	v_add_f32_e32 v219, v0, v219
	v_add_f32_e32 v219, v177, v219
	v_cvt_pk_fp8_f32 v253, v0, v177
	v_add_f32_e32 v219, v179, v219
	v_add_f32_e32 v219, v254, v219
	v_cvt_pk_fp8_f32 v253, v179, v254 op_sel:[0,0,1]
	ds_read_b128 v[90:93], v185 offset:8192
	ds_read_b128 v[94:97], v186 offset:8192
	ds_read_b128 v[82:85], v185 offset:10240
	ds_read_b128 v[86:89], v186 offset:10240
	ds_read_b128 v[74:77], v185 offset:12288
	ds_read_b128 v[78:81], v186 offset:12288
	ds_read_b128 v[66:69], v185 offset:14336
	ds_read_b128 v[70:73], v186 offset:14336
	s_waitcnt lgkmcnt(8)
	v_mfma_scale_f32_32x32x64_f8f6f4 v[98:113], v[222:229], v[130:137], v[98:113], v194, v193 op_sel_hi:[0,0,0]
	v_mov_b32_e32 v0, v219
	s_nop 1
	v_permlane32_swap_b32_e32 v219, v0
	v_add_f32_e32 v219, v219, v0
	v_fma_f32 v209, v209, v218, v219
	v_max_f32_e32 v177, v114, v115
	v_max3_f32 v177, v177, v116, v117
	v_max3_f32 v177, v177, v118, v119
	v_max3_f32 v177, v177, v120, v121
	v_max3_f32 v177, v177, v122, v123
	v_max3_f32 v177, v177, v124, v125
	v_max3_f32 v177, v177, v126, v127
	v_max3_f32 v177, v177, v128, v129
	s_waitcnt lgkmcnt(6)
	v_mfma_scale_f32_32x32x64_f8f6f4 v[50:65], v[246:253], v[90:97], v[50:65], v194, v194 op_sel_hi:[0,0,0]
	s_waitcnt lgkmcnt(4)
	v_mfma_scale_f32_32x32x64_f8f6f4 v[34:49], v[246:253], v[82:89], v[34:49], v194, v194 op_sel_hi:[0,0,0]
	s_waitcnt vmcnt(0)
	ds_write_b128 v210, v[158:161]
	ds_write_b128 v211, v[162:165] offset:16384
	ds_write_b128 v212, v[154:157] offset:32768
	s_waitcnt lgkmcnt(5)
	v_mfma_scale_f32_32x32x64_f8f6f4 v[18:33], v[246:253], v[74:81], v[18:33], v194, v194 op_sel_hi:[0,0,0]
	s_waitcnt lgkmcnt(3)
	v_mfma_scale_f32_32x32x64_f8f6f4 v[2:17], v[246:253], v[66:73], v[2:17], v194, v194 op_sel_hi:[0,0,0]
	s_waitcnt lgkmcnt(0)
	s_barrier
	v_max_f32_e32 v0, v98, v99
	v_max3_f32 v0, v0, v100, v101
	v_max3_f32 v0, v0, v102, v103
	v_max3_f32 v0, v0, v104, v105
	v_max3_f32 v0, v0, v106, v107
	v_max3_f32 v0, v0, v108, v109
	v_max3_f32 v0, v0, v110, v111
	v_max3_f32 v0, v0, v112, v113
	v_max_f32_e32 v177, v177, v0
	v_mov_b32_e32 v0, v177
	v_mov_b32_e32 v221, 1.0
	s_nop 0
	v_permlane32_swap_b32_e32 v177, v0
	v_max_f32_e32 v177, v177, v0
	v_cmp_ge_f32_e32 vcc, s90, v177
	s_cmp_eq_u64 vcc, exec
	s_cbranch_scc0 .Lmla_h4_newmax
; __device__ __forceinline__ void finishSM9(f32x16& p0, f32x16& p1, float alpha, float& l_reg, v8i32& p8) {
; #pragma unroll
;   for (int r = 0; r < 16; ++r) { p0[r] = __builtin_amdgcn_exp2f(p0[r]); p1[r] = __builtin_amdgcn_exp2f(p1[r]); }
;   float ps = 0;
; #pragma unroll
;   for (int r = 0; r < 16; ++r) ps += p0[r];
; #pragma unroll
;   for (int r = 0; r < 16; ++r) ps += p1[r];
;   { auto rr = __builtin_amdgcn_permlane32_swap(__float_as_uint(ps), __float_as_uint(ps), false, false);
;     ps = __uint_as_float(rr[0]) + __uint_as_float(rr[1]); }
;   l_reg = l_reg * alpha + ps;
; #pragma unroll
;   for (int g = 0; g < 4; ++g) {
;     int w = __builtin_amdgcn_cvt_pk_fp8_f32(p0[4 * g], p0[4 * g + 1], 0, false); p8[g] = __builtin_amdgcn_cvt_pk_fp8_f32(p0[4 * g + 2], p0[4 * g + 3], w, true);
;     int u = __builtin_amdgcn_cvt_pk_fp8_f32(p1[4 * g], p1[4 * g + 1], 0, false); p8[4 + g] = __builtin_amdgcn_cvt_pk_fp8_f32(p1[4 * g + 2], p1[4 * g + 3], u, true); }
; }
; __device__ __forceinline__ void pv8(f32x16* o, const char* Vt, const v8i32 p8, int r32, int hi) {
;   const int sw = (r32 >> 2) & 3, a0 = r32 * 64 + (((hi * 2) ^ sw) << 4), a1 = r32 * 64 + (((hi * 2 + 1) ^ sw) << 4);
; #pragma unroll
;   for (int d0 = 0; d0 < 4; ++d0) {
;     const v8i32 vf = cat8(*reinterpret_cast<const v4i32*>(Vt + d0 * 2048 + a0), *reinterpret_cast<const v4i32*>(Vt + d0 * 2048 + a1));
;     o[d0] = __builtin_amdgcn_mfma_scale_f32_32x32x64_f8f6f4(p8, vf, o[d0], 0, 0, 0, 127, 0, 127); }
; }
; __device__ __forceinline__ void qkt9(f32x16& p0, f32x16& p1, const char* Kn, const char* Kr, const v8i32* qf, const float init, int r32, int hi) {
; #pragma unroll
;   for (int r = 0; r < 16; ++r) { p0[r] = init; p1[r] = init; }
; #pragma unroll
;   for (int s = 0; s < 2; ++s) { const int c0 = s * 4 + hi * 2;
;     const v8i32 a0 = cat8(*reinterpret_cast<const v4i32*>(Kn + KN8SW(r32, c0)), *reinterpret_cast<const v4i32*>(Kn + KN8SW(r32, c0 + 1)));
;     const v8i32 a1 = cat8(*reinterpret_cast<const v4i32*>(Kn + 4096 + KN8SW(r32, c0)), *reinterpret_cast<const v4i32*>(Kn + 4096 + KN8SW(r32, c0 + 1)));
;     p0 = __builtin_amdgcn_mfma_scale_f32_32x32x64_f8f6f4(a0, qf[s], p0, 0, 0, 0, 127, 0, 124);
;     p1 = __builtin_amdgcn_mfma_scale_f32_32x32x64_f8f6f4(a1, qf[s], p1, 0, 0, 0, 127, 0, 124); }
;   { const int c0 = hi * 2;
.Lmla_h4_cont:
	ds_read_b128 v[82:85], v215 offset:16384
	ds_read_b128 v[86:89], v216 offset:16384
	ds_read_b128 v[222:225], v215 offset:20480
	ds_read_b128 v[226:229], v216 offset:20480
	global_load_dwordx4 v[158:161], v176, s[18:19]
	global_load_dwordx4 v[162:165], v178, s[16:17]
	global_load_dwordx4 v[154:157], v[180:181], off
	v_add_u32_e32 v176, 0x2000, v176
	v_add_u32_e32 v178, 0x20000, v178
	s_mov_b64 s[20:21], 0x1000
	v_lshl_add_u64 v[180:181], v[180:181], 0, s[20:21]
	v_exp_f32_e32 v0, v114
	v_exp_f32_e32 v177, v115
	v_exp_f32_e32 v179, v116
	v_exp_f32_e32 v254, v117
	v_add_f32_e32 v219, v0, v177
	v_cvt_pk_fp8_f32 v246, v0, v177
	v_add_f32_e32 v219, v179, v219
	v_add_f32_e32 v219, v254, v219
	v_cvt_pk_fp8_f32 v246, v179, v254 op_sel:[0,0,1]
	s_waitcnt lgkmcnt(2)
	v_mfma_scale_f32_32x32x64_f8f6f4 v[82:97], v[82:89], v[146:153], v[230:245], v194, v193 op_sel_hi:[0,0,0]
	v_exp_f32_e32 v0, v118
	v_exp_f32_e32 v177, v119
	v_exp_f32_e32 v179, v120
	v_exp_f32_e32 v254, v121
	v_add_f32_e32 v219, v0, v219
	v_add_f32_e32 v219, v177, v219
	v_cvt_pk_fp8_f32 v247, v0, v177
	v_add_f32_e32 v219, v179, v219
	v_add_f32_e32 v219, v254, v219
	v_cvt_pk_fp8_f32 v247, v179, v254 op_sel:[0,0,1]
	ds_read_b128 v[114:117], v213 offset:16384
	ds_read_b128 v[118:121], v214 offset:16384
	s_waitcnt lgkmcnt(2)
	v_mfma_scale_f32_32x32x64_f8f6f4 v[66:81], v[222:229], v[146:153], v[230:245], v194, v193 op_sel_hi:[0,0,0]
	ds_read_b128 v[222:225], v213 offset:20480
	ds_read_b128 v[226:229], v214 offset:20480
	v_exp_f32_e32 v0, v122
	v_exp_f32_e32 v177, v123
	v_exp_f32_e32 v179, v124
	v_exp_f32_e32 v254, v125
	v_add_f32_e32 v219, v0, v219
	v_add_f32_e32 v219, v177, v219
	v_cvt_pk_fp8_f32 v248, v0, v177
	v_add_f32_e32 v219, v179, v219
	v_add_f32_e32 v219, v254, v219
	v_cvt_pk_fp8_f32 v248, v179, v254 op_sel:[0,0,1]
	v_exp_f32_e32 v0, v126
	v_exp_f32_e32 v177, v127
	v_exp_f32_e32 v179, v128
	v_exp_f32_e32 v254, v129
	v_add_f32_e32 v219, v0, v219
	v_add_f32_e32 v219, v177, v219
	v_cvt_pk_fp8_f32 v249, v0, v177
	v_add_f32_e32 v219, v179, v219
	v_add_f32_e32 v219, v254, v219
	v_cvt_pk_fp8_f32 v249, v179, v254 op_sel:[0,0,1]
	ds_read_b128 v[122:125], v185 offset:32768
	ds_read_b128 v[126:129], v186 offset:32768
	s_waitcnt lgkmcnt(4)
	v_mfma_scale_f32_32x32x64_f8f6f4 v[82:97], v[114:121], v[138:145], v[82:97], v194, v193 op_sel_hi:[0,0,0]
	v_exp_f32_e32 v0, v98
	v_exp_f32_e32 v177, v99
	v_exp_f32_e32 v179, v100
	v_exp_f32_e32 v254, v101
	v_add_f32_e32 v219, v0, v219
	v_add_f32_e32 v219, v177, v219
	v_cvt_pk_fp8_f32 v250, v0, v177
	v_add_f32_e32 v219, v179, v219
	v_add_f32_e32 v219, v254, v219
	v_cvt_pk_fp8_f32 v250, v179, v254 op_sel:[0,0,1]
	s_waitcnt lgkmcnt(2)
	v_mfma_scale_f32_32x32x64_f8f6f4 v[66:81], v[222:229], v[138:145], v[66:81], v194, v193 op_sel_hi:[0,0,0]
	ds_read_b128 v[222:225], v185 offset:34816
	ds_read_b128 v[226:229], v186 offset:34816
	v_exp_f32_e32 v0, v102
	v_exp_f32_e32 v177, v103
	v_exp_f32_e32 v179, v104
	v_exp_f32_e32 v254, v105
	v_add_f32_e32 v219, v0, v219
	v_add_f32_e32 v219, v177, v219
	v_cvt_pk_fp8_f32 v251, v0, v177
	v_add_f32_e32 v219, v179, v219
	v_add_f32_e32 v219, v254, v219
	v_cvt_pk_fp8_f32 v251, v179, v254 op_sel:[0,0,1]
	v_exp_f32_e32 v0, v106
	v_exp_f32_e32 v177, v107
	v_exp_f32_e32 v179, v108
	v_exp_f32_e32 v254, v109
	v_add_f32_e32 v219, v0, v219
	v_add_f32_e32 v219, v177, v219
	v_cvt_pk_fp8_f32 v252, v0, v177
	v_add_f32_e32 v219, v179, v219
	v_add_f32_e32 v219, v254, v219
	v_cvt_pk_fp8_f32 v252, v179, v254 op_sel:[0,0,1]
	s_waitcnt lgkmcnt(2)
	v_mfma_scale_f32_32x32x64_f8f6f4 v[82:97], v[122:129], v[130:137], v[82:97], v194, v193 op_sel_hi:[0,0,0]
	v_exp_f32_e32 v0, v110
	v_exp_f32_e32 v177, v111
	v_exp_f32_e32 v179, v112
	v_exp_f32_e32 v254, v113
	v_add_f32_e32 v219, v0, v219
	v_add_f32_e32 v219, v177, v219
	v_cvt_pk_fp8_f32 v253, v0, v177
	v_add_f32_e32 v219, v179, v219
	v_add_f32_e32 v219, v254, v219
	v_cvt_pk_fp8_f32 v253, v179, v254 op_sel:[0,0,1]
	ds_read_b128 v[122:125], v185 offset:43008
	ds_read_b128 v[126:129], v186 offset:43008
	ds_read_b128 v[114:117], v185 offset:45056
	ds_read_b128 v[118:121], v186 offset:45056
	ds_read_b128 v[106:109], v185 offset:47104
	ds_read_b128 v[110:113], v186 offset:47104
	ds_read_b128 v[98:101], v185 offset:49152
	ds_read_b128 v[102:105], v186 offset:49152
	s_waitcnt lgkmcnt(8)
	v_mfma_scale_f32_32x32x64_f8f6f4 v[66:81], v[222:229], v[130:137], v[66:81], v194, v193 op_sel_hi:[0,0,0]
	v_mov_b32_e32 v0, v219
	s_nop 1
	v_permlane32_swap_b32_e32 v219, v0
	v_add_f32_e32 v219, v219, v0
	v_fma_f32 v209, v209, v221, v219
	v_max_f32_e32 v177, v82, v83
	v_max3_f32 v177, v177, v84, v85
	v_max3_f32 v177, v177, v86, v87
	v_max3_f32 v177, v177, v88, v89
	v_max3_f32 v177, v177, v90, v91
	v_max3_f32 v177, v177, v92, v93
	v_max3_f32 v177, v177, v94, v95
	v_max3_f32 v177, v177, v96, v97
	s_waitcnt lgkmcnt(6)
	v_mfma_scale_f32_32x32x64_f8f6f4 v[50:65], v[246:253], v[122:129], v[50:65], v194, v194 op_sel_hi:[0,0,0]
	s_waitcnt lgkmcnt(4)
	v_mfma_scale_f32_32x32x64_f8f6f4 v[34:49], v[246:253], v[114:121], v[34:49], v194, v194 op_sel_hi:[0,0,0]
	s_waitcnt vmcnt(0)
	ds_write_b128 v210, v[158:161] offset:8192
	ds_write_b128 v211, v[162:165] offset:24576
	ds_write_b128 v212, v[154:157] offset:36864
	s_waitcnt lgkmcnt(5)
	v_mfma_scale_f32_32x32x64_f8f6f4 v[18:33], v[246:253], v[106:113], v[18:33], v194, v194 op_sel_hi:[0,0,0]
	s_waitcnt lgkmcnt(3)
	v_mfma_scale_f32_32x32x64_f8f6f4 v[2:17], v[246:253], v[98:105], v[2:17], v194, v194 op_sel_hi:[0,0,0]
	s_waitcnt lgkmcnt(0)
	s_barrier
	v_max_f32_e32 v0, v66, v67
	v_max3_f32 v0, v0, v68, v69
	v_max3_f32 v0, v0, v70, v71
	v_max3_f32 v0, v0, v72, v73
	v_max3_f32 v0, v0, v74, v75
	v_max3_f32 v0, v0, v76, v77
	v_max3_f32 v0, v0, v78, v79
	v_max3_f32 v0, v0, v80, v81
	v_max_f32_e32 v177, v177, v0
	v_mov_b32_e32 v0, v177
	v_mov_b32_e32 v218, 1.0
	s_nop 0
	v_permlane32_swap_b32_e32 v177, v0
	v_max_f32_e32 v177, v177, v0
	v_cmp_ge_f32_e32 vcc, s90, v177
	s_cmp_eq_u64 vcc, exec
	s_cbranch_scc0 .Lmla_h5_newmax
; __device__ __forceinline__ void finishSM9(f32x16& p0, f32x16& p1, float alpha, float& l_reg, v8i32& p8) {
; #pragma unroll
;   for (int r = 0; r < 16; ++r) { p0[r] = __builtin_amdgcn_exp2f(p0[r]); p1[r] = __builtin_amdgcn_exp2f(p1[r]); }
;   float ps = 0;
; #pragma unroll
;   for (int r = 0; r < 16; ++r) ps += p0[r];
; #pragma unroll
;   for (int r = 0; r < 16; ++r) ps += p1[r];
;   { auto rr = __builtin_amdgcn_permlane32_swap(__float_as_uint(ps), __float_as_uint(ps), false, false);
;     ps = __uint_as_float(rr[0]) + __uint_as_float(rr[1]); }
;   l_reg = l_reg * alpha + ps;
; #pragma unroll
;   for (int g = 0; g < 4; ++g) {
;     int w = __builtin_amdgcn_cvt_pk_fp8_f32(p0[4 * g], p0[4 * g + 1], 0, false); p8[g] = __builtin_amdgcn_cvt_pk_fp8_f32(p0[4 * g + 2], p0[4 * g + 3], w, true);
;     int u = __builtin_amdgcn_cvt_pk_fp8_f32(p1[4 * g], p1[4 * g + 1], 0, false); p8[4 + g] = __builtin_amdgcn_cvt_pk_fp8_f32(p1[4 * g + 2], p1[4 * g + 3], u, true); }
; }
; __device__ __forceinline__ void pv8(f32x16* o, const char* Vt, const v8i32 p8, int r32, int hi) {
;   const int sw = (r32 >> 2) & 3, a0 = r32 * 64 + (((hi * 2) ^ sw) << 4), a1 = r32 * 64 + (((hi * 2 + 1) ^ sw) << 4);
; #pragma unroll
;   for (int d0 = 0; d0 < 4; ++d0) {
;     const v8i32 vf = cat8(*reinterpret_cast<const v4i32*>(Vt + d0 * 2048 + a0), *reinterpret_cast<const v4i32*>(Vt + d0 * 2048 + a1));
;     o[d0] = __builtin_amdgcn_mfma_scale_f32_32x32x64_f8f6f4(p8, vf, o[d0], 0, 0, 0, 127, 0, 127); }
; }
; __device__ __forceinline__ void qkt9(f32x16& p0, f32x16& p1, const char* Kn, const char* Kr, const v8i32* qf, const float init, int r32, int hi) {
; #pragma unroll
;   for (int r = 0; r < 16; ++r) { p0[r] = init; p1[r] = init; }
; #pragma unroll
;   for (int s = 0; s < 2; ++s) { const int c0 = s * 4 + hi * 2;
;     const v8i32 a0 = cat8(*reinterpret_cast<const v4i32*>(Kn + KN8SW(r32, c0)), *reinterpret_cast<const v4i32*>(Kn + KN8SW(r32, c0 + 1)));
;     const v8i32 a1 = cat8(*reinterpret_cast<const v4i32*>(Kn + 4096 + KN8SW(r32, c0)), *reinterpret_cast<const v4i32*>(Kn + 4096 + KN8SW(r32, c0 + 1)));
;     p0 = __builtin_amdgcn_mfma_scale_f32_32x32x64_f8f6f4(a0, qf[s], p0, 0, 0, 0, 127, 0, 124);
;     p1 = __builtin_amdgcn_mfma_scale_f32_32x32x64_f8f6f4(a1, qf[s], p1, 0, 0, 0, 127, 0, 124); }
;   { const int c0 = hi * 2;
.Lmla_h5_cont:
	s_add_i32 s30, s30, 1
	s_cmpk_lt_u32 s30, 42
	s_cbranch_scc1 .LBB0_1321
	ds_read_b128 v[114:117], v215 offset:24576
	ds_read_b128 v[118:121], v216 offset:24576
	ds_read_b128 v[222:225], v215 offset:28672
	ds_read_b128 v[226:229], v216 offset:28672
	global_load_dwordx4 v[158:161], v176, s[18:19]
	global_load_dwordx4 v[162:165], v178, s[16:17]
	global_load_dwordx4 v[154:157], v[180:181], off
	v_add_u32_e32 v176, 0x2000, v176
	v_add_u32_e32 v178, 0x20000, v178
	s_mov_b64 s[20:21], 0x1000
	v_lshl_add_u64 v[180:181], v[180:181], 0, s[20:21]
	v_exp_f32_e32 v0, v82
	v_exp_f32_e32 v177, v83
	v_exp_f32_e32 v179, v84
	v_exp_f32_e32 v254, v85
	v_add_f32_e32 v219, v0, v177
	v_cvt_pk_fp8_f32 v246, v0, v177
	v_add_f32_e32 v219, v179, v219
	v_add_f32_e32 v219, v254, v219
	v_cvt_pk_fp8_f32 v246, v179, v254 op_sel:[0,0,1]
	s_waitcnt lgkmcnt(2)
	v_mfma_scale_f32_32x32x64_f8f6f4 v[114:129], v[114:121], v[146:153], v[230:245], v194, v193 op_sel_hi:[0,0,0]
	v_exp_f32_e32 v0, v86
	v_exp_f32_e32 v177, v87
	v_exp_f32_e32 v179, v88
	v_exp_f32_e32 v254, v89
	v_add_f32_e32 v219, v0, v219
	v_add_f32_e32 v219, v177, v219
	v_cvt_pk_fp8_f32 v247, v0, v177
	v_add_f32_e32 v219, v179, v219
	v_add_f32_e32 v219, v254, v219
	v_cvt_pk_fp8_f32 v247, v179, v254 op_sel:[0,0,1]
	ds_read_b128 v[82:85], v213 offset:24576
	ds_read_b128 v[86:89], v214 offset:24576
	s_waitcnt lgkmcnt(2)
	v_mfma_scale_f32_32x32x64_f8f6f4 v[98:113], v[222:229], v[146:153], v[230:245], v194, v193 op_sel_hi:[0,0,0]
	ds_read_b128 v[222:225], v213 offset:28672
	ds_read_b128 v[226:229], v214 offset:28672
	v_exp_f32_e32 v0, v90
	v_exp_f32_e32 v177, v91
	v_exp_f32_e32 v179, v92
	v_exp_f32_e32 v254, v93
	v_add_f32_e32 v219, v0, v219
	v_add_f32_e32 v219, v177, v219
	v_cvt_pk_fp8_f32 v248, v0, v177
	v_add_f32_e32 v219, v179, v219
	v_add_f32_e32 v219, v254, v219
	v_cvt_pk_fp8_f32 v248, v179, v254 op_sel:[0,0,1]
	v_exp_f32_e32 v0, v94
	v_exp_f32_e32 v177, v95
	v_exp_f32_e32 v179, v96
	v_exp_f32_e32 v254, v97
	v_add_f32_e32 v219, v0, v219
	v_add_f32_e32 v219, v177, v219
	v_cvt_pk_fp8_f32 v249, v0, v177
	v_add_f32_e32 v219, v179, v219
	v_add_f32_e32 v219, v254, v219
	v_cvt_pk_fp8_f32 v249, v179, v254 op_sel:[0,0,1]
	ds_read_b128 v[90:93], v185 offset:36864
	ds_read_b128 v[94:97], v186 offset:36864
	s_waitcnt lgkmcnt(4)
	v_mfma_scale_f32_32x32x64_f8f6f4 v[114:129], v[82:89], v[138:145], v[114:129], v194, v193 op_sel_hi:[0,0,0]
	v_exp_f32_e32 v0, v66
	v_exp_f32_e32 v177, v67
	v_exp_f32_e32 v179, v68
	v_exp_f32_e32 v254, v69
	v_add_f32_e32 v219, v0, v219
	v_add_f32_e32 v219, v177, v219
	v_cvt_pk_fp8_f32 v250, v0, v177
	v_add_f32_e32 v219, v179, v219
	v_add_f32_e32 v219, v254, v219
	v_cvt_pk_fp8_f32 v250, v179, v254 op_sel:[0,0,1]
	s_waitcnt lgkmcnt(2)
	v_mfma_scale_f32_32x32x64_f8f6f4 v[98:113], v[222:229], v[138:145], v[98:113], v194, v193 op_sel_hi:[0,0,0]
	ds_read_b128 v[222:225], v185 offset:38912
	ds_read_b128 v[226:229], v186 offset:38912
	v_exp_f32_e32 v0, v70
	v_exp_f32_e32 v177, v71
	v_exp_f32_e32 v179, v72
	v_exp_f32_e32 v254, v73
	v_add_f32_e32 v219, v0, v219
	v_add_f32_e32 v219, v177, v219
	v_cvt_pk_fp8_f32 v251, v0, v177
	v_add_f32_e32 v219, v179, v219
	v_add_f32_e32 v219, v254, v219
	v_cvt_pk_fp8_f32 v251, v179, v254 op_sel:[0,0,1]
	v_exp_f32_e32 v0, v74
	v_exp_f32_e32 v177, v75
	v_exp_f32_e32 v179, v76
	v_exp_f32_e32 v254, v77
	v_add_f32_e32 v219, v0, v219
	v_add_f32_e32 v219, v177, v219
	v_cvt_pk_fp8_f32 v252, v0, v177
	v_add_f32_e32 v219, v179, v219
	v_add_f32_e32 v219, v254, v219
	v_cvt_pk_fp8_f32 v252, v179, v254 op_sel:[0,0,1]
	s_waitcnt lgkmcnt(2)
	v_mfma_scale_f32_32x32x64_f8f6f4 v[114:129], v[90:97], v[130:137], v[114:129], v194, v193 op_sel_hi:[0,0,0]
	v_exp_f32_e32 v0, v78
	v_exp_f32_e32 v177, v79
	v_exp_f32_e32 v179, v80
	v_exp_f32_e32 v254, v81
	v_add_f32_e32 v219, v0, v219
	v_add_f32_e32 v219, v177, v219
	v_cvt_pk_fp8_f32 v253, v0, v177
	v_add_f32_e32 v219, v179, v219
	v_add_f32_e32 v219, v254, v219
	v_cvt_pk_fp8_f32 v253, v179, v254 op_sel:[0,0,1]
	ds_read_b128 v[90:93], v185 offset:0
	ds_read_b128 v[94:97], v186 offset:0
	ds_read_b128 v[82:85], v185 offset:2048
	ds_read_b128 v[86:89], v186 offset:2048
	ds_read_b128 v[74:77], v185 offset:4096
	ds_read_b128 v[78:81], v186 offset:4096
	ds_read_b128 v[66:69], v185 offset:6144
	ds_read_b128 v[70:73], v186 offset:6144
	s_waitcnt lgkmcnt(8)
	v_mfma_scale_f32_32x32x64_f8f6f4 v[98:113], v[222:229], v[130:137], v[98:113], v194, v193 op_sel_hi:[0,0,0]
	v_mov_b32_e32 v0, v219
	s_nop 1
	v_permlane32_swap_b32_e32 v219, v0
	v_add_f32_e32 v219, v219, v0
	v_fma_f32 v209, v209, v218, v219
	v_max_f32_e32 v177, v114, v115
	v_max3_f32 v177, v177, v116, v117
	v_max3_f32 v177, v177, v118, v119
	v_max3_f32 v177, v177, v120, v121
	v_max3_f32 v177, v177, v122, v123
	v_max3_f32 v177, v177, v124, v125
	v_max3_f32 v177, v177, v126, v127
	v_max3_f32 v177, v177, v128, v129
	s_waitcnt lgkmcnt(6)
	v_mfma_scale_f32_32x32x64_f8f6f4 v[50:65], v[246:253], v[90:97], v[50:65], v194, v194 op_sel_hi:[0,0,0]
	s_waitcnt lgkmcnt(4)
	v_mfma_scale_f32_32x32x64_f8f6f4 v[34:49], v[246:253], v[82:89], v[34:49], v194, v194 op_sel_hi:[0,0,0]
	s_waitcnt vmcnt(0)
	ds_write_b128 v210, v[158:161] offset:43008
	ds_write_b128 v211, v[162:165] offset:51200
	ds_write_b128 v212, v[154:157] offset:59392
	s_waitcnt lgkmcnt(5)
	v_mfma_scale_f32_32x32x64_f8f6f4 v[18:33], v[246:253], v[74:81], v[18:33], v194, v194 op_sel_hi:[0,0,0]
	s_waitcnt lgkmcnt(3)
	v_mfma_scale_f32_32x32x64_f8f6f4 v[2:17], v[246:253], v[66:73], v[2:17], v194, v194 op_sel_hi:[0,0,0]
	s_waitcnt lgkmcnt(0)
	s_barrier
	v_max_f32_e32 v0, v98, v99
	v_max3_f32 v0, v0, v100, v101
	v_max3_f32 v0, v0, v102, v103
	v_max3_f32 v0, v0, v104, v105
	v_max3_f32 v0, v0, v106, v107
	v_max3_f32 v0, v0, v108, v109
	v_max3_f32 v0, v0, v110, v111
	v_max3_f32 v0, v0, v112, v113
	v_max_f32_e32 v177, v177, v0
	v_mov_b32_e32 v0, v177
	v_mov_b32_e32 v221, 1.0
	s_nop 0
	v_permlane32_swap_b32_e32 v177, v0
	v_max_f32_e32 v177, v177, v0
	v_cmp_ge_f32_e32 vcc, s90, v177
	s_cmp_eq_u64 vcc, exec
	s_cbranch_scc0 .Lmla_p0_newmax
